# odd-attention block loop hand-scheduled: interleaved QK chains, V double-buffer, early LDS reads, additive mask table, skip all-masked halves
# speedup vs baseline: 1.0108x; 1.0108x over previous
.LBB0_1083:
	v_mbcnt_lo_u32_b32 v0, -1, s1
	v_mbcnt_hi_u32_b32 v160, -1, v0
	s_lshl_b32 s1, s85, 13
	s_add_i32 s40, s1, 0x2800
	v_ashrrev_i32_e32 v2, 2, v160
	s_waitcnt lgkmcnt(0)
	s_add_u32 s22, s4, 0x9600000
	v_and_b32_e32 v166, -8, v2
	v_max_i32_e32 v2, 0x740, v160
	s_addc_u32 s23, s5, 0
	v_sub_u32_e32 v2, v2, v160
	s_add_u32 s41, s4, 0x100000
	s_movk_i32 s1, 0x780
	v_add_u32_e32 v2, 63, v2
	s_addc_u32 s42, s5, 0
	v_cmp_gt_i32_e64 s[6:7], s1, v160
	v_lshrrev_b32_e32 v3, 6, v2
	s_mov_b32 s1, 0x2aaaaaab
	s_add_u32 s43, s18, 0x2000000
	v_mul_hi_u32 v4, v3, s1
	s_addc_u32 s44, s19, 0
	v_mul_u32_u24_e32 v4, 6, v4
	s_add_u32 s24, s4, 0x7400000
	v_sub_u32_e32 v3, v3, v4
	s_addc_u32 s25, s5, 0
	v_ashrrev_i32_e32 v0, 5, v160
	v_and_b32_e32 v174, 31, v160
	v_add_u32_e32 v3, 1, v3
	v_ashrrev_i32_e32 v161, 31, v160
	v_lshlrev_b32_e32 v1, 2, v160
	v_lshlrev_b32_e32 v162, 3, v0
	v_lshlrev_b32_e32 v164, 3, v160
	v_lshlrev_b32_e32 v178, 2, v0
	v_sub_u32_e32 v0, 0, v174
	v_cmp_ne_u32_e64 s[10:11], 6, v3
	s_movk_i32 s1, 0x13f
	s_add_u32 s45, s4, 0x300000
	s_mov_b32 s0, -1
	s_mov_b32 s21, 0
	v_xor_b32_e32 v175, 0x80, v1
	v_ashrrev_i32_e32 v163, 31, v162
	v_max_u32_e32 v176, 8, v174
	v_min_u32_e32 v177, 24, v174
	v_ashrrev_i32_e32 v165, 31, v164
	v_cmp_gt_u32_e64 s[8:9], 32, v160
	v_ashrrev_i32_e32 v167, 31, v166
	v_cndmask_b32_e64 v179, 0, v3, s[10:11]
	v_cmp_lt_u32_e64 s[12:13], s1, v2
	v_add_u32_e32 v180, s40, v1
	s_addc_u32 s46, s5, 0
	v_mov_b32_e32 v169, 0
	s_movk_i32 s47, 0x5ff
	v_lshlrev_b64 v[170:171], 2, v[160:161]
	s_movk_i32 s48, 0x1800
	s_mov_b32 s49, 0x30000
	v_lshlrev_b32_e32 v161, 2, v0
	s_movk_i32 s50, 0xffef
	s_movk_i32 s51, 0xffe0
	s_mov_b64 s[26:27], 0x10000
	s_mov_b32 s52, 0x10000
	v_not_b32_e32 v181, 47
	v_mov_b32_e32 v182, 0xf149f2ca
	v_mov_b32_e32 v183, 0
	v_lshlrev_b32_e32 v168, 4, v160
	v_sub_u32_e32 v186, v178, v176
	v_add_u32_e32 v186, 8, v186
	v_sub_u32_e32 v187, v178, v177
	v_add_u32_e32 v187, 8, v187
	v_add_u32_e32 v188, 0, v186
	v_cmp_gt_u32_e32 vcc, 16, v188
	s_nop 1
	v_cndmask_b32_e32 v190, v182, v169, vcc
	v_add_u32_e32 v188, 1, v186
	v_cmp_gt_u32_e32 vcc, 16, v188
	s_nop 1
	v_cndmask_b32_e32 v191, v182, v169, vcc
	v_add_u32_e32 v188, 2, v186
	v_cmp_gt_u32_e32 vcc, 16, v188
	s_nop 1
	v_cndmask_b32_e32 v192, v182, v169, vcc
	v_add_u32_e32 v188, 3, v186
	v_cmp_gt_u32_e32 vcc, 16, v188
	s_nop 1
	v_cndmask_b32_e32 v193, v182, v169, vcc
	ds_write_b128 v168, v[190:193] offset:0
	s_nop 1
	v_add_u32_e32 v188, 8, v186
	v_cmp_gt_u32_e32 vcc, 16, v188
	s_nop 1
	v_cndmask_b32_e32 v190, v182, v169, vcc
	v_add_u32_e32 v188, 9, v186
	v_cmp_gt_u32_e32 vcc, 16, v188
	s_nop 1
	v_cndmask_b32_e32 v191, v182, v169, vcc
	v_add_u32_e32 v188, 10, v186
	v_cmp_gt_u32_e32 vcc, 16, v188
	s_nop 1
	v_cndmask_b32_e32 v192, v182, v169, vcc
	v_add_u32_e32 v188, 11, v186
	v_cmp_gt_u32_e32 vcc, 16, v188
	s_nop 1
	v_cndmask_b32_e32 v193, v182, v169, vcc
	ds_write_b128 v168, v[190:193] offset:1024
	s_nop 1
	v_add_u32_e32 v188, 16, v186
	v_cmp_gt_u32_e32 vcc, 16, v188
	s_nop 1
	v_cndmask_b32_e32 v190, v182, v169, vcc
	v_add_u32_e32 v188, 17, v186
	v_cmp_gt_u32_e32 vcc, 16, v188
	s_nop 1
	v_cndmask_b32_e32 v191, v182, v169, vcc
	v_add_u32_e32 v188, 18, v186
	v_cmp_gt_u32_e32 vcc, 16, v188
	s_nop 1
	v_cndmask_b32_e32 v192, v182, v169, vcc
	v_add_u32_e32 v188, 19, v186
	v_cmp_gt_u32_e32 vcc, 16, v188
	s_nop 1
	v_cndmask_b32_e32 v193, v182, v169, vcc
	ds_write_b128 v168, v[190:193] offset:2048
	s_nop 1
	v_add_u32_e32 v188, 24, v186
	v_cmp_gt_u32_e32 vcc, 16, v188
	s_nop 1
	v_cndmask_b32_e32 v190, v182, v169, vcc
	v_add_u32_e32 v188, 25, v186
	v_cmp_gt_u32_e32 vcc, 16, v188
	s_nop 1
	v_cndmask_b32_e32 v191, v182, v169, vcc
	v_add_u32_e32 v188, 26, v186
	v_cmp_gt_u32_e32 vcc, 16, v188
	s_nop 1
	v_cndmask_b32_e32 v192, v182, v169, vcc
	v_add_u32_e32 v188, 27, v186
	v_cmp_gt_u32_e32 vcc, 16, v188
	s_nop 1
	v_cndmask_b32_e32 v193, v182, v169, vcc
	ds_write_b128 v168, v[190:193] offset:3072
	s_nop 1
	v_add_u32_e32 v188, 0, v187
	v_cmp_gt_u32_e32 vcc, 16, v188
	s_nop 1
	v_cndmask_b32_e32 v190, v182, v169, vcc
	v_add_u32_e32 v188, 1, v187
	v_cmp_gt_u32_e32 vcc, 16, v188
	s_nop 1
	v_cndmask_b32_e32 v191, v182, v169, vcc
	v_add_u32_e32 v188, 2, v187
	v_cmp_gt_u32_e32 vcc, 16, v188
	s_nop 1
	v_cndmask_b32_e32 v192, v182, v169, vcc
	v_add_u32_e32 v188, 3, v187
	v_cmp_gt_u32_e32 vcc, 16, v188
	s_nop 1
	v_cndmask_b32_e32 v193, v182, v169, vcc
	ds_write_b128 v168, v[190:193] offset:4096
	s_nop 1
	v_add_u32_e32 v188, 8, v187
	v_cmp_gt_u32_e32 vcc, 16, v188
	s_nop 1
	v_cndmask_b32_e32 v190, v182, v169, vcc
	v_add_u32_e32 v188, 9, v187
	v_cmp_gt_u32_e32 vcc, 16, v188
	s_nop 1
	v_cndmask_b32_e32 v191, v182, v169, vcc
	v_add_u32_e32 v188, 10, v187
	v_cmp_gt_u32_e32 vcc, 16, v188
	s_nop 1
	v_cndmask_b32_e32 v192, v182, v169, vcc
	v_add_u32_e32 v188, 11, v187
	v_cmp_gt_u32_e32 vcc, 16, v188
	s_nop 1
	v_cndmask_b32_e32 v193, v182, v169, vcc
	ds_write_b128 v168, v[190:193] offset:5120
	s_nop 1
	v_add_u32_e32 v188, 16, v187
	v_cmp_gt_u32_e32 vcc, 16, v188
	s_nop 1
	v_cndmask_b32_e32 v190, v182, v169, vcc
	v_add_u32_e32 v188, 17, v187
	v_cmp_gt_u32_e32 vcc, 16, v188
	s_nop 1
	v_cndmask_b32_e32 v191, v182, v169, vcc
	v_add_u32_e32 v188, 18, v187
	v_cmp_gt_u32_e32 vcc, 16, v188
	s_nop 1
	v_cndmask_b32_e32 v192, v182, v169, vcc
	v_add_u32_e32 v188, 19, v187
	v_cmp_gt_u32_e32 vcc, 16, v188
	s_nop 1
	v_cndmask_b32_e32 v193, v182, v169, vcc
	ds_write_b128 v168, v[190:193] offset:6144
	s_nop 1
	v_add_u32_e32 v188, 24, v187
	v_cmp_gt_u32_e32 vcc, 16, v188
	s_nop 1
	v_cndmask_b32_e32 v190, v182, v169, vcc
	v_add_u32_e32 v188, 25, v187
	v_cmp_gt_u32_e32 vcc, 16, v188
	s_nop 1
	v_cndmask_b32_e32 v191, v182, v169, vcc
	v_add_u32_e32 v188, 26, v187
	v_cmp_gt_u32_e32 vcc, 16, v188
	s_nop 1
	v_cndmask_b32_e32 v192, v182, v169, vcc
	v_add_u32_e32 v188, 27, v187
	v_cmp_gt_u32_e32 vcc, 16, v188
	s_nop 1
	v_cndmask_b32_e32 v193, v182, v169, vcc
	ds_write_b128 v168, v[190:193] offset:7168
	s_nop 1
	v_add_u32_e32 v188, 32, v186
	v_cmp_gt_u32_e64 s[58:59], 16, v188
	v_add_u32_e32 v188, 33, v186
	v_cmp_gt_u32_e64 s[60:61], 16, v188
	v_add_u32_e32 v188, 34, v186
	v_cmp_gt_u32_e64 s[62:63], 16, v188
	v_add_u32_e32 v188, 35, v186
	v_cmp_gt_u32_e64 s[64:65], 16, v188
	v_add_u32_e32 v188, -8, v187
	v_cmp_gt_u32_e64 s[66:67], 16, v188
	v_add_u32_e32 v188, -7, v187
	v_cmp_gt_u32_e64 s[94:95], 16, v188
	v_add_u32_e32 v188, -6, v187
	v_cmp_gt_u32_e64 s[96:97], 16, v188
	v_add_u32_e32 v188, -5, v187
	v_cmp_gt_u32_e64 s[98:99], 16, v188
	s_waitcnt lgkmcnt(0)
	s_branch .LBB0_1085

.LBB0_1097:
	s_lshr_b32 s1, s90, 6
	s_and_b32 s1, s1, 15
	s_and_b32 s17, s90, 63
	s_waitcnt lgkmcnt(0)
	s_ashr_i32 s28, s90, 10
	s_lshl_b32 s16, s1, 3
	s_lshl_b32 s1, s28, 12
	s_lshl_b32 s2, s17, 6
	s_or_b32 s1, s1, s2
	v_or_b32_e32 v172, s1, v174
	v_mov_b64_e32 v[0:1], s[22:23]
	v_mad_i64_i32 v[0:1], s[4:5], v172, s48, v[0:1]
	s_lshl_b32 s20, s33, 7
	v_lshl_add_u64 v[0:1], v[0:1], 0, s[20:21]
	v_lshl_add_u64 v[0:1], v[162:163], 1, v[0:1]
	s_waitcnt lgkmcnt(0)
	v_add_co_u32_e32 v2, vcc, s49, v0
	s_lshl_b32 s4, s28, 4
	s_nop 0
	v_addc_co_u32_e32 v3, vcc, 0, v1, vcc
	global_load_dwordx4 v[96:99], v[0:1], off
	global_load_dwordx4 v[100:103], v[0:1], off offset:32
	global_load_dwordx4 v[104:107], v[2:3], off
	global_load_dwordx4 v[108:111], v[2:3], off offset:32
	global_load_dwordx4 v[112:115], v[0:1], off offset:64
	global_load_dwordx4 v[116:119], v[0:1], off offset:96
	global_load_dwordx4 v[120:123], v[2:3], off offset:64
	global_load_dwordx4 v[124:127], v[2:3], off offset:96
	v_sub_u32_e64 v0, s17, 4 clamp
	s_or_b32 s14, s4, s33
	v_readfirstlane_b32 s4, v0
	s_min_u32 s20, s4, 56
	s_lshl_b32 s4, s14, 3
	s_ashr_i32 s5, s4, 31
	s_lshl_b32 s1, s33, 6
	s_lshl_b64 s[4:5], s[4:5], 12
	s_add_u32 s4, s41, s4
	s_addc_u32 s5, s42, s5
	v_lshl_add_u64 v[0:1], v[164:165], 1, s[4:5]
	global_load_dwordx4 v[136:139], v[0:1], off
	global_load_dwordx4 v[132:135], v[0:1], off offset:1024
	global_load_dwordx4 v[140:143], v[0:1], off offset:2048
	global_load_dwordx4 v[128:131], v[0:1], off offset:3072
	s_ashr_i32 s15, s14, 31
	s_lshl_b64 s[14:15], s[14:15], 19
	s_lshl_b32 s29, s20, 13
	s_or_b32 s14, s14, s29
	s_add_u32 s33, s18, s14
	s_addc_u32 s34, s19, s15
	s_add_u32 s35, s43, s14
	s_addc_u32 s36, s44, s15
	s_lshl_b32 s14, s28, 7
	s_or_b32 s14, s14, s16
	s_ashr_i32 s15, s14, 31
	s_sub_i32 s37, s20, s17
	s_lshl_b64 s[14:15], s[14:15], 12
	v_xor_b32_e32 v48, 0x80000000, v183
	s_add_u32 s14, s45, s14
	v_mov_b32_e32 v185, 0
	v_ashrrev_i32_e32 v173, 31, v172
	s_mov_b32 s2, 0
	v_mov_b32_e32 v49, v48
	v_mov_b32_e32 v50, v48
	v_mov_b32_e32 v51, v48
	v_mov_b32_e32 v52, v48
	v_mov_b32_e32 v53, v48
	v_mov_b32_e32 v54, v48
	v_mov_b32_e32 v55, v48
	v_mov_b32_e32 v56, v48
	v_mov_b32_e32 v57, v48
	v_mov_b32_e32 v58, v48
	v_mov_b32_e32 v59, v48
	v_mov_b32_e32 v60, v48
	v_mov_b32_e32 v61, v48
	v_mov_b32_e32 v62, v48
	v_mov_b32_e32 v63, v48
	s_addc_u32 s15, s46, s15
	s_mov_b32 s16, -8
	s_mov_b32 s39, 0
	v_mov_b32_e32 v184, 0
	v_mov_b32_e32 v32, 0
	v_mov_b32_e32 v33, v185
	v_mov_b32_e32 v34, v185
	v_mov_b32_e32 v35, v185
	v_mov_b32_e32 v36, v185
	v_mov_b32_e32 v37, v185
	v_mov_b32_e32 v38, v185
	v_mov_b32_e32 v39, v185
	v_mov_b32_e32 v40, v185
	v_mov_b32_e32 v41, v185
	v_mov_b32_e32 v42, v185
	v_mov_b32_e32 v43, v185
	v_mov_b32_e32 v44, v185
	v_mov_b32_e32 v45, v185
	v_mov_b32_e32 v46, v185
	v_mov_b32_e32 v47, v185
	v_mov_b32_e32 v64, 0
	v_mov_b32_e32 v65, v185
	v_mov_b32_e32 v66, v185
	v_mov_b32_e32 v67, v185
	v_mov_b32_e32 v68, v185
	v_mov_b32_e32 v69, v185
	v_mov_b32_e32 v70, v185
	v_mov_b32_e32 v71, v185
	v_mov_b32_e32 v72, v185
	v_mov_b32_e32 v73, v185
	v_mov_b32_e32 v74, v185
	v_mov_b32_e32 v75, v185
	v_mov_b32_e32 v76, v185
	v_mov_b32_e32 v77, v185
	v_mov_b32_e32 v78, v185
	v_mov_b32_e32 v79, v185
	v_mov_b32_e32 v16, 0
	v_mov_b32_e32 v17, v185
	v_mov_b32_e32 v18, v185
	v_mov_b32_e32 v19, v185
	v_mov_b32_e32 v20, v185
	v_mov_b32_e32 v21, v185
	v_mov_b32_e32 v22, v185
	v_mov_b32_e32 v23, v185
	v_mov_b32_e32 v24, v185
	v_mov_b32_e32 v25, v185
	v_mov_b32_e32 v26, v185
	v_mov_b32_e32 v27, v185
	v_mov_b32_e32 v28, v185
	v_mov_b32_e32 v29, v185
	v_mov_b32_e32 v30, v185
	v_mov_b32_e32 v31, v185
	v_mov_b32_e32 v0, 0
	v_mov_b32_e32 v1, v185
	v_mov_b32_e32 v2, v185
	v_mov_b32_e32 v3, v185
	v_mov_b32_e32 v4, v185
	v_mov_b32_e32 v5, v185
	v_mov_b32_e32 v6, v185
	v_mov_b32_e32 v7, v185
	v_mov_b32_e32 v8, v185
	v_mov_b32_e32 v9, v185
	v_mov_b32_e32 v10, v185
	v_mov_b32_e32 v11, v185
	v_mov_b32_e32 v12, v185
	v_mov_b32_e32 v13, v185
	v_mov_b32_e32 v14, v185
	v_mov_b32_e32 v15, v185
	v_lshlrev_b32_e32 v168, 4, v160
	v_lshl_add_u32 v255, v178, 2, v161
	s_lshl_b32 s68, s37, 9
	s_add_i32 s68, s68, s40
	s_addk_i32 s68, 0xe7c
	v_add_u32_e32 v255, s68, v255
	global_load_dwordx4 v[144:147], v168, s[14:15]
	global_load_dwordx4 v[148:151], v168, s[14:15] offset:1024
	global_load_dwordx4 v[152:155], v168, s[14:15] offset:2048
	global_load_dwordx4 v[156:159], v168, s[14:15] offset:3072
	s_add_u32 s54, s4, 0x1000
	s_addc_u32 s55, s5, 0
	s_add_u32 s56, s14, 0x1000
	s_addc_u32 s57, s15, 0
	s_mov_b32 s53, 0
.Lao_ctx_loop:
	s_waitcnt vmcnt(4)
	v_mfma_f32_32x32x16_bf16 v[80:95], v[136:139], v[96:99], v[48:63]
	v_mfma_f32_32x32x16_bf16 v[216:231], v[136:139], v[104:107], v[48:63]
	v_mfma_f32_32x32x16_bf16 v[80:95], v[132:135], v[100:103], v[80:95]
	v_mfma_f32_32x32x16_bf16 v[216:231], v[132:135], v[108:111], v[216:231]
	v_mfma_f32_32x32x16_bf16 v[80:95], v[140:143], v[112:115], v[80:95]
	v_mfma_f32_32x32x16_bf16 v[216:231], v[140:143], v[120:123], v[216:231]
	v_mfma_f32_32x32x16_bf16 v[80:95], v[128:131], v[116:119], v[80:95]
	v_mfma_f32_32x32x16_bf16 v[216:231], v[128:131], v[124:127], v[216:231]
	global_load_dwordx4 v[136:139], v168, s[54:55]
	global_load_dwordx4 v[132:135], v168, s[54:55] offset:1024
	global_load_dwordx4 v[140:143], v168, s[54:55] offset:2048
	global_load_dwordx4 v[128:131], v168, s[54:55] offset:3072
	global_load_dwordx4 v[232:235], v168, s[56:57]
	global_load_dwordx4 v[236:239], v168, s[56:57] offset:1024
	global_load_dwordx4 v[240:243], v168, s[56:57] offset:2048
	global_load_dwordx4 v[244:247], v168, s[56:57] offset:3072
	s_add_u32 s54, s54, 0x1000
	s_addc_u32 s55, s55, 0
	s_add_u32 s56, s56, 0x1000
	s_addc_u32 s57, s57, 0
	v_exp_f32_e32 v80, v80
	v_exp_f32_e32 v81, v81
	v_exp_f32_e32 v82, v82
	v_exp_f32_e32 v83, v83
	v_exp_f32_e32 v84, v84
	v_exp_f32_e32 v85, v85
	v_exp_f32_e32 v86, v86
	v_exp_f32_e32 v87, v87
	v_exp_f32_e32 v88, v88
	v_exp_f32_e32 v89, v89
	v_exp_f32_e32 v90, v90
	v_exp_f32_e32 v91, v91
	v_exp_f32_e32 v92, v92
	v_exp_f32_e32 v93, v93
	v_exp_f32_e32 v94, v94
	v_exp_f32_e32 v95, v95
	v_pk_add_f32 v[186:187], v[80:81], v[82:83]
	v_pk_add_f32 v[188:189], v[84:85], v[86:87]
	v_pk_add_f32 v[190:191], v[88:89], v[90:91]
	v_pk_add_f32 v[192:193], v[92:93], v[94:95]
	v_pk_add_f32 v[186:187], v[186:187], v[188:189]
	v_pk_add_f32 v[190:191], v[190:191], v[192:193]
	v_pk_add_f32 v[186:187], v[186:187], v[190:191]
	v_add_f32_e32 v186, v186, v187
	v_add_f32_e32 v185, v185, v186
	v_cvt_pk_bf16_f32 v80, v80, v81
	v_cvt_pk_bf16_f32 v81, v82, v83
	v_cvt_pk_bf16_f32 v82, v84, v85
	v_cvt_pk_bf16_f32 v83, v86, v87
	v_cvt_pk_bf16_f32 v84, v88, v89
	v_cvt_pk_bf16_f32 v85, v90, v91
	v_cvt_pk_bf16_f32 v86, v92, v93
	v_cvt_pk_bf16_f32 v87, v94, v95
	s_waitcnt vmcnt(8)
	s_nop 0
	v_mfma_f32_32x32x16_bf16 v[64:79], v[144:147], v[80:83], v[64:79]
	v_mfma_f32_32x32x16_bf16 v[32:47], v[148:151], v[80:83], v[32:47]
	v_mfma_f32_32x32x16_bf16 v[64:79], v[152:155], v[84:87], v[64:79]
	v_mfma_f32_32x32x16_bf16 v[32:47], v[156:159], v[84:87], v[32:47]
	v_exp_f32_e32 v216, v216
	v_exp_f32_e32 v217, v217
	v_exp_f32_e32 v218, v218
	v_exp_f32_e32 v219, v219
	v_exp_f32_e32 v220, v220
	v_exp_f32_e32 v221, v221
	v_exp_f32_e32 v222, v222
	v_exp_f32_e32 v223, v223
	v_exp_f32_e32 v224, v224
	v_exp_f32_e32 v225, v225
	v_exp_f32_e32 v226, v226
	v_exp_f32_e32 v227, v227
	v_exp_f32_e32 v228, v228
	v_exp_f32_e32 v229, v229
	v_exp_f32_e32 v230, v230
	v_exp_f32_e32 v231, v231
	v_pk_add_f32 v[194:195], v[216:217], v[218:219]
	v_pk_add_f32 v[196:197], v[220:221], v[222:223]
	v_pk_add_f32 v[198:199], v[224:225], v[226:227]
	v_pk_add_f32 v[200:201], v[228:229], v[230:231]
	v_pk_add_f32 v[194:195], v[194:195], v[196:197]
	v_pk_add_f32 v[198:199], v[198:199], v[200:201]
	v_pk_add_f32 v[194:195], v[194:195], v[198:199]
	v_add_f32_e32 v194, v194, v195
	v_add_f32_e32 v184, v184, v194
	v_cvt_pk_bf16_f32 v216, v216, v217
	v_cvt_pk_bf16_f32 v217, v218, v219
	v_cvt_pk_bf16_f32 v218, v220, v221
	v_cvt_pk_bf16_f32 v219, v222, v223
	v_cvt_pk_bf16_f32 v220, v224, v225
	v_cvt_pk_bf16_f32 v221, v226, v227
	v_cvt_pk_bf16_f32 v222, v228, v229
	v_cvt_pk_bf16_f32 v223, v230, v231
	s_nop 1
	v_mfma_f32_32x32x16_bf16 v[16:31], v[144:147], v[216:219], v[16:31]
	v_mfma_f32_32x32x16_bf16 v[0:15], v[148:151], v[216:219], v[0:15]
	v_mfma_f32_32x32x16_bf16 v[16:31], v[152:155], v[220:223], v[16:31]
	v_mfma_f32_32x32x16_bf16 v[0:15], v[156:159], v[220:223], v[0:15]
	s_cmp_eq_u32 s53, 3
	s_cselect_b32 s54, s33, s54
	s_cselect_b32 s55, s34, s55
	s_cselect_b32 s56, s35, s56
	s_cselect_b32 s57, s36, s57
	s_waitcnt vmcnt(4)
	v_mfma_f32_32x32x16_bf16 v[80:95], v[136:139], v[96:99], v[48:63]
	v_mfma_f32_32x32x16_bf16 v[216:231], v[136:139], v[104:107], v[48:63]
	v_mfma_f32_32x32x16_bf16 v[80:95], v[132:135], v[100:103], v[80:95]
	v_mfma_f32_32x32x16_bf16 v[216:231], v[132:135], v[108:111], v[216:231]
	v_mfma_f32_32x32x16_bf16 v[80:95], v[140:143], v[112:115], v[80:95]
	v_mfma_f32_32x32x16_bf16 v[216:231], v[140:143], v[120:123], v[216:231]
	v_mfma_f32_32x32x16_bf16 v[80:95], v[128:131], v[116:119], v[80:95]
	v_mfma_f32_32x32x16_bf16 v[216:231], v[128:131], v[124:127], v[216:231]
	global_load_dwordx4 v[136:139], v168, s[54:55]
	global_load_dwordx4 v[132:135], v168, s[54:55] offset:1024
	global_load_dwordx4 v[140:143], v168, s[54:55] offset:2048
	global_load_dwordx4 v[128:131], v168, s[54:55] offset:3072
	global_load_dwordx4 v[144:147], v168, s[56:57]
	global_load_dwordx4 v[148:151], v168, s[56:57] offset:1024
	global_load_dwordx4 v[152:155], v168, s[56:57] offset:2048
	global_load_dwordx4 v[156:159], v168, s[56:57] offset:3072
	s_add_u32 s54, s54, 0x1000
	s_addc_u32 s55, s55, 0
	s_add_u32 s56, s56, 0x1000
	s_addc_u32 s57, s57, 0
	v_exp_f32_e32 v80, v80
	v_exp_f32_e32 v81, v81
	v_exp_f32_e32 v82, v82
	v_exp_f32_e32 v83, v83
	v_exp_f32_e32 v84, v84
	v_exp_f32_e32 v85, v85
	v_exp_f32_e32 v86, v86
	v_exp_f32_e32 v87, v87
	v_exp_f32_e32 v88, v88
	v_exp_f32_e32 v89, v89
	v_exp_f32_e32 v90, v90
	v_exp_f32_e32 v91, v91
	v_exp_f32_e32 v92, v92
	v_exp_f32_e32 v93, v93
	v_exp_f32_e32 v94, v94
	v_exp_f32_e32 v95, v95
	v_pk_add_f32 v[186:187], v[80:81], v[82:83]
	v_pk_add_f32 v[188:189], v[84:85], v[86:87]
	v_pk_add_f32 v[190:191], v[88:89], v[90:91]
	v_pk_add_f32 v[192:193], v[92:93], v[94:95]
	v_pk_add_f32 v[186:187], v[186:187], v[188:189]
	v_pk_add_f32 v[190:191], v[190:191], v[192:193]
	v_pk_add_f32 v[186:187], v[186:187], v[190:191]
	v_add_f32_e32 v186, v186, v187
	v_add_f32_e32 v185, v185, v186
	v_cvt_pk_bf16_f32 v80, v80, v81
	v_cvt_pk_bf16_f32 v81, v82, v83
	v_cvt_pk_bf16_f32 v82, v84, v85
	v_cvt_pk_bf16_f32 v83, v86, v87
	v_cvt_pk_bf16_f32 v84, v88, v89
	v_cvt_pk_bf16_f32 v85, v90, v91
	v_cvt_pk_bf16_f32 v86, v92, v93
	v_cvt_pk_bf16_f32 v87, v94, v95
	s_waitcnt vmcnt(8)
	s_nop 0
	v_mfma_f32_32x32x16_bf16 v[64:79], v[232:235], v[80:83], v[64:79]
	v_mfma_f32_32x32x16_bf16 v[32:47], v[236:239], v[80:83], v[32:47]
	v_mfma_f32_32x32x16_bf16 v[64:79], v[240:243], v[84:87], v[64:79]
	v_mfma_f32_32x32x16_bf16 v[32:47], v[244:247], v[84:87], v[32:47]
	v_exp_f32_e32 v216, v216
	v_exp_f32_e32 v217, v217
	v_exp_f32_e32 v218, v218
	v_exp_f32_e32 v219, v219
	v_exp_f32_e32 v220, v220
	v_exp_f32_e32 v221, v221
	v_exp_f32_e32 v222, v222
	v_exp_f32_e32 v223, v223
	v_exp_f32_e32 v224, v224
	v_exp_f32_e32 v225, v225
	v_exp_f32_e32 v226, v226
	v_exp_f32_e32 v227, v227
	v_exp_f32_e32 v228, v228
	v_exp_f32_e32 v229, v229
	v_exp_f32_e32 v230, v230
	v_exp_f32_e32 v231, v231
	v_pk_add_f32 v[194:195], v[216:217], v[218:219]
	v_pk_add_f32 v[196:197], v[220:221], v[222:223]
	v_pk_add_f32 v[198:199], v[224:225], v[226:227]
	v_pk_add_f32 v[200:201], v[228:229], v[230:231]
	v_pk_add_f32 v[194:195], v[194:195], v[196:197]
	v_pk_add_f32 v[198:199], v[198:199], v[200:201]
	v_pk_add_f32 v[194:195], v[194:195], v[198:199]
	v_add_f32_e32 v194, v194, v195
	v_add_f32_e32 v184, v184, v194
	v_cvt_pk_bf16_f32 v216, v216, v217
	v_cvt_pk_bf16_f32 v217, v218, v219
	v_cvt_pk_bf16_f32 v218, v220, v221
	v_cvt_pk_bf16_f32 v219, v222, v223
	v_cvt_pk_bf16_f32 v220, v224, v225
	v_cvt_pk_bf16_f32 v221, v226, v227
	v_cvt_pk_bf16_f32 v222, v228, v229
	v_cvt_pk_bf16_f32 v223, v230, v231
	s_nop 1
	v_mfma_f32_32x32x16_bf16 v[16:31], v[232:235], v[216:219], v[16:31]
	v_mfma_f32_32x32x16_bf16 v[0:15], v[236:239], v[216:219], v[0:15]
	v_mfma_f32_32x32x16_bf16 v[16:31], v[240:243], v[220:223], v[16:31]
	v_mfma_f32_32x32x16_bf16 v[0:15], v[244:247], v[220:223], v[0:15]
	s_add_i32 s53, s53, 1
	s_cmp_lt_u32 s53, 4
	s_cbranch_scc1 .Lao_ctx_loop
	s_mov_b32 s53, 0
.Lao_win_loop:
	ds_read2_b32 v[186:187], v255 offset0:32 offset1:33
	ds_read2_b32 v[188:189], v255 offset0:34 offset1:35
	ds_read2_b32 v[190:191], v255 offset0:40 offset1:41
	ds_read2_b32 v[192:193], v255 offset0:42 offset1:43
	ds_read2_b32 v[194:195], v255 offset0:48 offset1:49
	ds_read2_b32 v[196:197], v255 offset0:50 offset1:51
	ds_read2_b32 v[198:199], v255 offset0:56 offset1:57
	ds_read2_b32 v[200:201], v255 offset0:58 offset1:59
	ds_read_b128 v[204:207], v168 offset:0
	ds_read_b128 v[208:211], v168 offset:1024
	ds_read_b128 v[212:215], v168 offset:2048
	ds_read_b128 v[248:251], v168 offset:3072
	ds_read2_b32 v[202:203], v255 offset0:24 offset1:25
	ds_read2_b32 v[252:253], v255 offset0:26 offset1:27
	s_waitcnt vmcnt(4)
	v_mfma_f32_32x32x16_bf16 v[80:95], v[136:139], v[96:99], v[48:63]
	v_mfma_f32_32x32x16_bf16 v[216:231], v[136:139], v[104:107], v[48:63]
	v_mfma_f32_32x32x16_bf16 v[80:95], v[132:135], v[100:103], v[80:95]
	v_mfma_f32_32x32x16_bf16 v[216:231], v[132:135], v[108:111], v[216:231]
	v_mfma_f32_32x32x16_bf16 v[80:95], v[140:143], v[112:115], v[80:95]
	v_mfma_f32_32x32x16_bf16 v[216:231], v[140:143], v[120:123], v[216:231]
	v_mfma_f32_32x32x16_bf16 v[80:95], v[128:131], v[116:119], v[80:95]
	v_mfma_f32_32x32x16_bf16 v[216:231], v[128:131], v[124:127], v[216:231]
	global_load_dwordx4 v[136:139], v168, s[54:55]
	global_load_dwordx4 v[132:135], v168, s[54:55] offset:1024
	global_load_dwordx4 v[140:143], v168, s[54:55] offset:2048
	global_load_dwordx4 v[128:131], v168, s[54:55] offset:3072
	global_load_dwordx4 v[232:235], v168, s[56:57]
	global_load_dwordx4 v[236:239], v168, s[56:57] offset:1024
	global_load_dwordx4 v[240:243], v168, s[56:57] offset:2048
	global_load_dwordx4 v[244:247], v168, s[56:57] offset:3072
	s_add_u32 s54, s54, 0x1000
	s_addc_u32 s55, s55, 0
	s_add_u32 s56, s56, 0x1000
	s_addc_u32 s57, s57, 0
	s_waitcnt lgkmcnt(2)
	v_pk_add_f32 v[80:81], v[80:81], v[186:187]
	v_pk_add_f32 v[82:83], v[82:83], v[188:189]
	v_pk_add_f32 v[84:85], v[84:85], v[190:191]
	v_pk_add_f32 v[86:87], v[86:87], v[192:193]
	v_pk_add_f32 v[88:89], v[88:89], v[194:195]
	v_pk_add_f32 v[90:91], v[90:91], v[196:197]
	v_pk_add_f32 v[92:93], v[92:93], v[198:199]
	v_pk_add_f32 v[94:95], v[94:95], v[200:201]
	v_pk_add_f32 v[80:81], v[80:81], v[204:205]
	v_pk_add_f32 v[82:83], v[82:83], v[206:207]
	v_pk_add_f32 v[84:85], v[84:85], v[208:209]
	v_pk_add_f32 v[86:87], v[86:87], v[210:211]
	v_pk_add_f32 v[88:89], v[88:89], v[212:213]
	v_pk_add_f32 v[90:91], v[90:91], v[214:215]
	v_pk_add_f32 v[92:93], v[92:93], v[248:249]
	v_pk_add_f32 v[94:95], v[94:95], v[250:251]
	v_exp_f32_e32 v80, v80
	v_exp_f32_e32 v81, v81
	v_exp_f32_e32 v82, v82
	v_exp_f32_e32 v83, v83
	v_exp_f32_e32 v84, v84
	v_exp_f32_e32 v85, v85
	v_exp_f32_e32 v86, v86
	v_exp_f32_e32 v87, v87
	v_exp_f32_e32 v88, v88
	v_exp_f32_e32 v89, v89
	v_exp_f32_e32 v90, v90
	v_exp_f32_e32 v91, v91
	v_exp_f32_e32 v92, v92
	v_exp_f32_e32 v93, v93
	v_exp_f32_e32 v94, v94
	v_exp_f32_e32 v95, v95
	v_pk_add_f32 v[186:187], v[80:81], v[82:83]
	v_pk_add_f32 v[188:189], v[84:85], v[86:87]
	v_pk_add_f32 v[190:191], v[88:89], v[90:91]
	v_pk_add_f32 v[192:193], v[92:93], v[94:95]
	v_pk_add_f32 v[186:187], v[186:187], v[188:189]
	v_pk_add_f32 v[190:191], v[190:191], v[192:193]
	v_pk_add_f32 v[186:187], v[186:187], v[190:191]
	v_add_f32_e32 v186, v186, v187
	v_add_f32_e32 v185, v185, v186
	v_cvt_pk_bf16_f32 v80, v80, v81
	v_cvt_pk_bf16_f32 v81, v82, v83
	v_cvt_pk_bf16_f32 v82, v84, v85
	v_cvt_pk_bf16_f32 v83, v86, v87
	v_cvt_pk_bf16_f32 v84, v88, v89
	v_cvt_pk_bf16_f32 v85, v90, v91
	v_cvt_pk_bf16_f32 v86, v92, v93
	v_cvt_pk_bf16_f32 v87, v94, v95
	s_waitcnt vmcnt(8)
	s_nop 0
	v_mfma_f32_32x32x16_bf16 v[64:79], v[144:147], v[80:83], v[64:79]
	v_mfma_f32_32x32x16_bf16 v[32:47], v[148:151], v[80:83], v[32:47]
	v_mfma_f32_32x32x16_bf16 v[64:79], v[152:155], v[84:87], v[64:79]
	v_mfma_f32_32x32x16_bf16 v[32:47], v[156:159], v[84:87], v[32:47]
	s_waitcnt lgkmcnt(0)
	v_pk_add_f32 v[228:229], v[228:229], v[202:203]
	v_pk_add_f32 v[230:231], v[230:231], v[252:253]
	v_cndmask_b32_e64 v228, v182, v228, s[66:67]
	v_cndmask_b32_e64 v229, v182, v229, s[94:95]
	v_cndmask_b32_e64 v230, v182, v230, s[96:97]
	v_cndmask_b32_e64 v231, v182, v231, s[98:99]
	v_exp_f32_e32 v228, v228
	v_exp_f32_e32 v229, v229
	v_exp_f32_e32 v230, v230
	v_exp_f32_e32 v231, v231
	v_mov_b32_e32 v224, 0
	v_mov_b32_e32 v225, 0
	v_pk_add_f32 v[202:203], v[228:229], v[230:231]
	v_cvt_pk_bf16_f32 v226, v228, v229
	v_cvt_pk_bf16_f32 v227, v230, v231
	v_add_f32_e32 v202, v202, v203
	v_add_f32_e32 v184, v184, v202
	s_nop 1
	v_mfma_f32_32x32x16_bf16 v[16:31], v[152:155], v[224:227], v[16:31]
	v_mfma_f32_32x32x16_bf16 v[0:15], v[156:159], v[224:227], v[0:15]
	ds_read2_b32 v[202:203], v255 offset0:64 offset1:65
	ds_read2_b32 v[252:253], v255 offset0:66 offset1:67
	ds_read2_b32 v[186:187], v255 offset0:32 offset1:33
	ds_read2_b32 v[188:189], v255 offset0:34 offset1:35
	ds_read2_b32 v[190:191], v255 offset0:40 offset1:41
	ds_read2_b32 v[192:193], v255 offset0:42 offset1:43
	ds_read2_b32 v[194:195], v255 offset0:48 offset1:49
	ds_read2_b32 v[196:197], v255 offset0:50 offset1:51
	ds_read2_b32 v[198:199], v255 offset0:56 offset1:57
	ds_read2_b32 v[200:201], v255 offset0:58 offset1:59
	ds_read_b128 v[204:207], v168 offset:4096
	ds_read_b128 v[208:211], v168 offset:5120
	ds_read_b128 v[212:215], v168 offset:6144
	ds_read_b128 v[248:251], v168 offset:7168
	v_add_u32_e32 v255, 0x200, v255
	s_waitcnt vmcnt(4)
	v_mfma_f32_32x32x16_bf16 v[80:95], v[136:139], v[96:99], v[48:63]
	v_mfma_f32_32x32x16_bf16 v[216:231], v[136:139], v[104:107], v[48:63]
	v_mfma_f32_32x32x16_bf16 v[80:95], v[132:135], v[100:103], v[80:95]
	v_mfma_f32_32x32x16_bf16 v[216:231], v[132:135], v[108:111], v[216:231]
	v_mfma_f32_32x32x16_bf16 v[80:95], v[140:143], v[112:115], v[80:95]
	v_mfma_f32_32x32x16_bf16 v[216:231], v[140:143], v[120:123], v[216:231]
	v_mfma_f32_32x32x16_bf16 v[80:95], v[128:131], v[116:119], v[80:95]
	v_mfma_f32_32x32x16_bf16 v[216:231], v[128:131], v[124:127], v[216:231]
	global_load_dwordx4 v[136:139], v168, s[54:55]
	global_load_dwordx4 v[132:135], v168, s[54:55] offset:1024
	global_load_dwordx4 v[140:143], v168, s[54:55] offset:2048
	global_load_dwordx4 v[128:131], v168, s[54:55] offset:3072
	global_load_dwordx4 v[144:147], v168, s[56:57]
	global_load_dwordx4 v[148:151], v168, s[56:57] offset:1024
	global_load_dwordx4 v[152:155], v168, s[56:57] offset:2048
	global_load_dwordx4 v[156:159], v168, s[56:57] offset:3072
	s_add_u32 s54, s54, 0x1000
	s_addc_u32 s55, s55, 0
	s_add_u32 s56, s56, 0x1000
	s_addc_u32 s57, s57, 0
	s_waitcnt lgkmcnt(12)
	v_pk_add_f32 v[80:81], v[80:81], v[202:203]
	v_pk_add_f32 v[82:83], v[82:83], v[252:253]
	v_cndmask_b32_e64 v80, v182, v80, s[58:59]
	v_cndmask_b32_e64 v81, v182, v81, s[60:61]
	v_cndmask_b32_e64 v82, v182, v82, s[62:63]
	v_cndmask_b32_e64 v83, v182, v83, s[64:65]
	v_exp_f32_e32 v80, v80
	v_exp_f32_e32 v81, v81
	v_exp_f32_e32 v82, v82
	v_exp_f32_e32 v83, v83
	s_nop 0
	v_pk_add_f32 v[202:203], v[80:81], v[82:83]
	v_cvt_pk_bf16_f32 v80, v80, v81
	v_cvt_pk_bf16_f32 v81, v82, v83
	v_mov_b32_e32 v82, 0
	v_mov_b32_e32 v83, 0
	v_add_f32_e32 v202, v202, v203
	v_add_f32_e32 v185, v185, v202
	s_waitcnt vmcnt(8)
	s_nop 0
	v_mfma_f32_32x32x16_bf16 v[64:79], v[232:235], v[80:83], v[64:79]
	v_mfma_f32_32x32x16_bf16 v[32:47], v[236:239], v[80:83], v[32:47]
	s_waitcnt lgkmcnt(0)
	v_pk_add_f32 v[216:217], v[216:217], v[186:187]
	v_pk_add_f32 v[218:219], v[218:219], v[188:189]
	v_pk_add_f32 v[220:221], v[220:221], v[190:191]
	v_pk_add_f32 v[222:223], v[222:223], v[192:193]
	v_pk_add_f32 v[224:225], v[224:225], v[194:195]
	v_pk_add_f32 v[226:227], v[226:227], v[196:197]
	v_pk_add_f32 v[228:229], v[228:229], v[198:199]
	v_pk_add_f32 v[230:231], v[230:231], v[200:201]
	v_pk_add_f32 v[216:217], v[216:217], v[204:205]
	v_pk_add_f32 v[218:219], v[218:219], v[206:207]
	v_pk_add_f32 v[220:221], v[220:221], v[208:209]
	v_pk_add_f32 v[222:223], v[222:223], v[210:211]
	v_pk_add_f32 v[224:225], v[224:225], v[212:213]
	v_pk_add_f32 v[226:227], v[226:227], v[214:215]
	v_pk_add_f32 v[228:229], v[228:229], v[248:249]
	v_pk_add_f32 v[230:231], v[230:231], v[250:251]
	v_exp_f32_e32 v216, v216
	v_exp_f32_e32 v217, v217
	v_exp_f32_e32 v218, v218
	v_exp_f32_e32 v219, v219
	v_exp_f32_e32 v220, v220
	v_exp_f32_e32 v221, v221
	v_exp_f32_e32 v222, v222
	v_exp_f32_e32 v223, v223
	v_exp_f32_e32 v224, v224
	v_exp_f32_e32 v225, v225
	v_exp_f32_e32 v226, v226
	v_exp_f32_e32 v227, v227
	v_exp_f32_e32 v228, v228
	v_exp_f32_e32 v229, v229
	v_exp_f32_e32 v230, v230
	v_exp_f32_e32 v231, v231
	v_pk_add_f32 v[186:187], v[216:217], v[218:219]
	v_pk_add_f32 v[188:189], v[220:221], v[222:223]
	v_pk_add_f32 v[190:191], v[224:225], v[226:227]
	v_pk_add_f32 v[192:193], v[228:229], v[230:231]
	v_pk_add_f32 v[186:187], v[186:187], v[188:189]
	v_pk_add_f32 v[190:191], v[190:191], v[192:193]
	v_pk_add_f32 v[186:187], v[186:187], v[190:191]
	v_add_f32_e32 v186, v186, v187
	v_add_f32_e32 v184, v184, v186
	v_cvt_pk_bf16_f32 v216, v216, v217
	v_cvt_pk_bf16_f32 v217, v218, v219
	v_cvt_pk_bf16_f32 v218, v220, v221
	v_cvt_pk_bf16_f32 v219, v222, v223
	v_cvt_pk_bf16_f32 v220, v224, v225
	v_cvt_pk_bf16_f32 v221, v226, v227
	v_cvt_pk_bf16_f32 v222, v228, v229
	v_cvt_pk_bf16_f32 v223, v230, v231
	s_nop 1
	v_mfma_f32_32x32x16_bf16 v[16:31], v[232:235], v[216:219], v[16:31]
	v_mfma_f32_32x32x16_bf16 v[0:15], v[236:239], v[216:219], v[0:15]
	v_mfma_f32_32x32x16_bf16 v[16:31], v[240:243], v[220:223], v[16:31]
	v_mfma_f32_32x32x16_bf16 v[0:15], v[244:247], v[220:223], v[0:15]
	s_add_i32 s53, s53, 1
	s_cmp_lt_u32 s53, 7
	s_cbranch_scc1 .Lao_win_loop
	ds_read2_b32 v[186:187], v255 offset0:32 offset1:33
	ds_read2_b32 v[188:189], v255 offset0:34 offset1:35
	ds_read2_b32 v[190:191], v255 offset0:40 offset1:41
	ds_read2_b32 v[192:193], v255 offset0:42 offset1:43
	ds_read2_b32 v[194:195], v255 offset0:48 offset1:49
	ds_read2_b32 v[196:197], v255 offset0:50 offset1:51
	ds_read2_b32 v[198:199], v255 offset0:56 offset1:57
	ds_read2_b32 v[200:201], v255 offset0:58 offset1:59
	ds_read_b128 v[204:207], v168 offset:0
	ds_read_b128 v[208:211], v168 offset:1024
	ds_read_b128 v[212:215], v168 offset:2048
	ds_read_b128 v[248:251], v168 offset:3072
	ds_read2_b32 v[202:203], v255 offset0:24 offset1:25
	ds_read2_b32 v[252:253], v255 offset0:26 offset1:27
	s_waitcnt vmcnt(4)
	v_mfma_f32_32x32x16_bf16 v[80:95], v[136:139], v[96:99], v[48:63]
	v_mfma_f32_32x32x16_bf16 v[216:231], v[136:139], v[104:107], v[48:63]
	v_mfma_f32_32x32x16_bf16 v[80:95], v[132:135], v[100:103], v[80:95]
	v_mfma_f32_32x32x16_bf16 v[216:231], v[132:135], v[108:111], v[216:231]
	v_mfma_f32_32x32x16_bf16 v[80:95], v[140:143], v[112:115], v[80:95]
	v_mfma_f32_32x32x16_bf16 v[216:231], v[140:143], v[120:123], v[216:231]
	v_mfma_f32_32x32x16_bf16 v[80:95], v[128:131], v[116:119], v[80:95]
	v_mfma_f32_32x32x16_bf16 v[216:231], v[128:131], v[124:127], v[216:231]
	global_load_dwordx4 v[136:139], v168, s[54:55]
	global_load_dwordx4 v[132:135], v168, s[54:55] offset:1024
	global_load_dwordx4 v[140:143], v168, s[54:55] offset:2048
	global_load_dwordx4 v[128:131], v168, s[54:55] offset:3072
	global_load_dwordx4 v[232:235], v168, s[56:57]
	global_load_dwordx4 v[236:239], v168, s[56:57] offset:1024
	global_load_dwordx4 v[240:243], v168, s[56:57] offset:2048
	global_load_dwordx4 v[244:247], v168, s[56:57] offset:3072
	s_add_u32 s54, s54, 0x1000
	s_addc_u32 s55, s55, 0
	s_add_u32 s56, s56, 0x1000
	s_addc_u32 s57, s57, 0
	s_waitcnt lgkmcnt(2)
	v_pk_add_f32 v[80:81], v[80:81], v[186:187]
	v_pk_add_f32 v[82:83], v[82:83], v[188:189]
	v_pk_add_f32 v[84:85], v[84:85], v[190:191]
	v_pk_add_f32 v[86:87], v[86:87], v[192:193]
	v_pk_add_f32 v[88:89], v[88:89], v[194:195]
	v_pk_add_f32 v[90:91], v[90:91], v[196:197]
	v_pk_add_f32 v[92:93], v[92:93], v[198:199]
	v_pk_add_f32 v[94:95], v[94:95], v[200:201]
	v_pk_add_f32 v[80:81], v[80:81], v[204:205]
	v_pk_add_f32 v[82:83], v[82:83], v[206:207]
	v_pk_add_f32 v[84:85], v[84:85], v[208:209]
	v_pk_add_f32 v[86:87], v[86:87], v[210:211]
	v_pk_add_f32 v[88:89], v[88:89], v[212:213]
	v_pk_add_f32 v[90:91], v[90:91], v[214:215]
	v_pk_add_f32 v[92:93], v[92:93], v[248:249]
	v_pk_add_f32 v[94:95], v[94:95], v[250:251]
	v_exp_f32_e32 v80, v80
	v_exp_f32_e32 v81, v81
	v_exp_f32_e32 v82, v82
	v_exp_f32_e32 v83, v83
	v_exp_f32_e32 v84, v84
	v_exp_f32_e32 v85, v85
	v_exp_f32_e32 v86, v86
	v_exp_f32_e32 v87, v87
	v_exp_f32_e32 v88, v88
	v_exp_f32_e32 v89, v89
	v_exp_f32_e32 v90, v90
	v_exp_f32_e32 v91, v91
	v_exp_f32_e32 v92, v92
	v_exp_f32_e32 v93, v93
	v_exp_f32_e32 v94, v94
	v_exp_f32_e32 v95, v95
	v_pk_add_f32 v[186:187], v[80:81], v[82:83]
	v_pk_add_f32 v[188:189], v[84:85], v[86:87]
	v_pk_add_f32 v[190:191], v[88:89], v[90:91]
	v_pk_add_f32 v[192:193], v[92:93], v[94:95]
	v_pk_add_f32 v[186:187], v[186:187], v[188:189]
	v_pk_add_f32 v[190:191], v[190:191], v[192:193]
	v_pk_add_f32 v[186:187], v[186:187], v[190:191]
	v_add_f32_e32 v186, v186, v187
	v_add_f32_e32 v185, v185, v186
	v_cvt_pk_bf16_f32 v80, v80, v81
	v_cvt_pk_bf16_f32 v81, v82, v83
	v_cvt_pk_bf16_f32 v82, v84, v85
	v_cvt_pk_bf16_f32 v83, v86, v87
	v_cvt_pk_bf16_f32 v84, v88, v89
	v_cvt_pk_bf16_f32 v85, v90, v91
	v_cvt_pk_bf16_f32 v86, v92, v93
	v_cvt_pk_bf16_f32 v87, v94, v95
	s_waitcnt vmcnt(8)
	s_nop 0
	v_mfma_f32_32x32x16_bf16 v[64:79], v[144:147], v[80:83], v[64:79]
	v_mfma_f32_32x32x16_bf16 v[32:47], v[148:151], v[80:83], v[32:47]
	v_mfma_f32_32x32x16_bf16 v[64:79], v[152:155], v[84:87], v[64:79]
	v_mfma_f32_32x32x16_bf16 v[32:47], v[156:159], v[84:87], v[32:47]
	s_waitcnt lgkmcnt(0)
	v_pk_add_f32 v[228:229], v[228:229], v[202:203]
	v_pk_add_f32 v[230:231], v[230:231], v[252:253]
	v_cndmask_b32_e64 v228, v182, v228, s[66:67]
	v_cndmask_b32_e64 v229, v182, v229, s[94:95]
	v_cndmask_b32_e64 v230, v182, v230, s[96:97]
	v_cndmask_b32_e64 v231, v182, v231, s[98:99]
	v_exp_f32_e32 v228, v228
	v_exp_f32_e32 v229, v229
	v_exp_f32_e32 v230, v230
	v_exp_f32_e32 v231, v231
	v_mov_b32_e32 v224, 0
	v_mov_b32_e32 v225, 0
	v_pk_add_f32 v[202:203], v[228:229], v[230:231]
	v_cvt_pk_bf16_f32 v226, v228, v229
	v_cvt_pk_bf16_f32 v227, v230, v231
	v_add_f32_e32 v202, v202, v203
	v_add_f32_e32 v184, v184, v202
	s_nop 1
	v_mfma_f32_32x32x16_bf16 v[16:31], v[152:155], v[224:227], v[16:31]
	v_mfma_f32_32x32x16_bf16 v[0:15], v[156:159], v[224:227], v[0:15]
	ds_read2_b32 v[202:203], v255 offset0:64 offset1:65
	ds_read2_b32 v[252:253], v255 offset0:66 offset1:67
	ds_read2_b32 v[186:187], v255 offset0:32 offset1:33
	ds_read2_b32 v[188:189], v255 offset0:34 offset1:35
	ds_read2_b32 v[190:191], v255 offset0:40 offset1:41
	ds_read2_b32 v[192:193], v255 offset0:42 offset1:43
	ds_read2_b32 v[194:195], v255 offset0:48 offset1:49
	ds_read2_b32 v[196:197], v255 offset0:50 offset1:51
	ds_read2_b32 v[198:199], v255 offset0:56 offset1:57
	ds_read2_b32 v[200:201], v255 offset0:58 offset1:59
	ds_read_b128 v[204:207], v168 offset:4096
	ds_read_b128 v[208:211], v168 offset:5120
	ds_read_b128 v[212:215], v168 offset:6144
	ds_read_b128 v[248:251], v168 offset:7168
	v_add_u32_e32 v255, 0x200, v255
	s_waitcnt vmcnt(4)
	v_mfma_f32_32x32x16_bf16 v[80:95], v[136:139], v[96:99], v[48:63]
	v_mfma_f32_32x32x16_bf16 v[216:231], v[136:139], v[104:107], v[48:63]
	v_mfma_f32_32x32x16_bf16 v[80:95], v[132:135], v[100:103], v[80:95]
	v_mfma_f32_32x32x16_bf16 v[216:231], v[132:135], v[108:111], v[216:231]
	v_mfma_f32_32x32x16_bf16 v[80:95], v[140:143], v[112:115], v[80:95]
	v_mfma_f32_32x32x16_bf16 v[216:231], v[140:143], v[120:123], v[216:231]
	v_mfma_f32_32x32x16_bf16 v[80:95], v[128:131], v[116:119], v[80:95]
	v_mfma_f32_32x32x16_bf16 v[216:231], v[128:131], v[124:127], v[216:231]
	s_nop 10
	s_waitcnt lgkmcnt(12)
	v_pk_add_f32 v[80:81], v[80:81], v[202:203]
	v_pk_add_f32 v[82:83], v[82:83], v[252:253]
	v_cndmask_b32_e64 v80, v182, v80, s[58:59]
	v_cndmask_b32_e64 v81, v182, v81, s[60:61]
	v_cndmask_b32_e64 v82, v182, v82, s[62:63]
	v_cndmask_b32_e64 v83, v182, v83, s[64:65]
	v_exp_f32_e32 v80, v80
	v_exp_f32_e32 v81, v81
	v_exp_f32_e32 v82, v82
	v_exp_f32_e32 v83, v83
	s_nop 0
	v_pk_add_f32 v[202:203], v[80:81], v[82:83]
	v_cvt_pk_bf16_f32 v80, v80, v81
	v_cvt_pk_bf16_f32 v81, v82, v83
	v_mov_b32_e32 v82, 0
	v_mov_b32_e32 v83, 0
	v_add_f32_e32 v202, v202, v203
	v_add_f32_e32 v185, v185, v202
	s_waitcnt vmcnt(0)
	s_nop 0
	v_mfma_f32_32x32x16_bf16 v[64:79], v[232:235], v[80:83], v[64:79]
	v_mfma_f32_32x32x16_bf16 v[32:47], v[236:239], v[80:83], v[32:47]
	s_waitcnt lgkmcnt(0)
	v_pk_add_f32 v[216:217], v[216:217], v[186:187]
	v_pk_add_f32 v[218:219], v[218:219], v[188:189]
	v_pk_add_f32 v[220:221], v[220:221], v[190:191]
	v_pk_add_f32 v[222:223], v[222:223], v[192:193]
	v_pk_add_f32 v[224:225], v[224:225], v[194:195]
	v_pk_add_f32 v[226:227], v[226:227], v[196:197]
	v_pk_add_f32 v[228:229], v[228:229], v[198:199]
	v_pk_add_f32 v[230:231], v[230:231], v[200:201]
	v_pk_add_f32 v[216:217], v[216:217], v[204:205]
	v_pk_add_f32 v[218:219], v[218:219], v[206:207]
	v_pk_add_f32 v[220:221], v[220:221], v[208:209]
	v_pk_add_f32 v[222:223], v[222:223], v[210:211]
	v_pk_add_f32 v[224:225], v[224:225], v[212:213]
	v_pk_add_f32 v[226:227], v[226:227], v[214:215]
	v_pk_add_f32 v[228:229], v[228:229], v[248:249]
	v_pk_add_f32 v[230:231], v[230:231], v[250:251]
	v_exp_f32_e32 v216, v216
	v_exp_f32_e32 v217, v217
	v_exp_f32_e32 v218, v218
	v_exp_f32_e32 v219, v219
	v_exp_f32_e32 v220, v220
	v_exp_f32_e32 v221, v221
	v_exp_f32_e32 v222, v222
	v_exp_f32_e32 v223, v223
	v_exp_f32_e32 v224, v224
	v_exp_f32_e32 v225, v225
	v_exp_f32_e32 v226, v226
	v_exp_f32_e32 v227, v227
	v_exp_f32_e32 v228, v228
	v_exp_f32_e32 v229, v229
	v_exp_f32_e32 v230, v230
	v_exp_f32_e32 v231, v231
	v_pk_add_f32 v[186:187], v[216:217], v[218:219]
	v_pk_add_f32 v[188:189], v[220:221], v[222:223]
	v_pk_add_f32 v[190:191], v[224:225], v[226:227]
	v_pk_add_f32 v[192:193], v[228:229], v[230:231]
	v_pk_add_f32 v[186:187], v[186:187], v[188:189]
	v_pk_add_f32 v[190:191], v[190:191], v[192:193]
	v_pk_add_f32 v[186:187], v[186:187], v[190:191]
	v_add_f32_e32 v186, v186, v187
	v_add_f32_e32 v184, v184, v186
	v_cvt_pk_bf16_f32 v216, v216, v217
	v_cvt_pk_bf16_f32 v217, v218, v219
	v_cvt_pk_bf16_f32 v218, v220, v221
	v_cvt_pk_bf16_f32 v219, v222, v223
	v_cvt_pk_bf16_f32 v220, v224, v225
	v_cvt_pk_bf16_f32 v221, v226, v227
	v_cvt_pk_bf16_f32 v222, v228, v229
	v_cvt_pk_bf16_f32 v223, v230, v231
	s_nop 1
	v_mfma_f32_32x32x16_bf16 v[16:31], v[232:235], v[216:219], v[16:31]
	v_mfma_f32_32x32x16_bf16 v[0:15], v[236:239], v[216:219], v[0:15]
	v_mfma_f32_32x32x16_bf16 v[16:31], v[240:243], v[220:223], v[16:31]
	v_mfma_f32_32x32x16_bf16 v[0:15], v[244:247], v[220:223], v[0:15]
	s_branch .LBB0_1084

	.amdhsa_kernel _Z8mega_fwd6Params
		.amdhsa_group_segment_fixed_size 0
		.amdhsa_private_segment_fixed_size 0
		.amdhsa_kernarg_size 440
		.amdhsa_user_sgpr_count 2
		.amdhsa_user_sgpr_dispatch_ptr 0
		.amdhsa_user_sgpr_queue_ptr 0
		.amdhsa_user_sgpr_kernarg_segment_ptr 1
		.amdhsa_user_sgpr_dispatch_id 0
		.amdhsa_user_sgpr_kernarg_preload_length 0
		.amdhsa_user_sgpr_kernarg_preload_offset 0
		.amdhsa_user_sgpr_private_segment_size 0
		.amdhsa_uses_dynamic_stack 0
		.amdhsa_enable_private_segment 0
		.amdhsa_system_sgpr_workgroup_id_x 1
		.amdhsa_system_sgpr_workgroup_id_y 0
		.amdhsa_system_sgpr_workgroup_id_z 0
		.amdhsa_system_sgpr_workgroup_info 0
		.amdhsa_system_vgpr_workitem_id 2
		.amdhsa_next_free_vgpr 256
		.amdhsa_next_free_sgpr 102
		.amdhsa_accum_offset 256
		.amdhsa_reserve_vcc 1
		.amdhsa_float_round_mode_32 0
		.amdhsa_float_round_mode_16_64 0
		.amdhsa_float_denorm_mode_32 3
		.amdhsa_float_denorm_mode_16_64 3
		.amdhsa_dx10_clamp 1
		.amdhsa_ieee_mode 1
		.amdhsa_fp16_overflow 0
		.amdhsa_tg_split 0
		.amdhsa_exception_fp_ieee_invalid_op 0
		.amdhsa_exception_fp_denorm_src 0
		.amdhsa_exception_fp_ieee_div_zero 0
		.amdhsa_exception_fp_ieee_overflow 0
		.amdhsa_exception_fp_ieee_underflow 0
		.amdhsa_exception_fp_ieee_inexact 0
		.amdhsa_exception_int_div_zero 0
	.end_amdhsa_kernel

amdhsa.kernels:
  - .agpr_count:     0
    .args:
      - .offset:         0
        .size:           184
        .value_kind:     by_value
      - .offset:         184
        .size:           4
        .value_kind:     hidden_block_count_x
      - .offset:         188
        .size:           4
        .value_kind:     hidden_block_count_y
      - .offset:         192
        .size:           4
        .value_kind:     hidden_block_count_z
      - .offset:         196
        .size:           2
        .value_kind:     hidden_group_size_x
      - .offset:         198
        .size:           2
        .value_kind:     hidden_group_size_y
      - .offset:         200
        .size:           2
        .value_kind:     hidden_group_size_z
      - .offset:         202
        .size:           2
        .value_kind:     hidden_remainder_x
      - .offset:         204
        .size:           2
        .value_kind:     hidden_remainder_y
      - .offset:         206
        .size:           2
        .value_kind:     hidden_remainder_z
      - .offset:         224
        .size:           8
        .value_kind:     hidden_global_offset_x
      - .offset:         232
        .size:           8
        .value_kind:     hidden_global_offset_y
      - .offset:         240
        .size:           8
        .value_kind:     hidden_global_offset_z
      - .offset:         248
        .size:           2
        .value_kind:     hidden_grid_dims
      - .offset:         272
        .size:           8
        .value_kind:     hidden_multigrid_sync_arg
      - .offset:         304
        .size:           4
        .value_kind:     hidden_dynamic_lds_size
    .group_segment_fixed_size: 0
    .kernarg_segment_align: 8
    .kernarg_segment_size: 440
    .language:       OpenCL C
    .language_version:
      - 2
      - 0
    .max_flat_workgroup_size: 512
    .name:           _Z8mega_fwd6Params
    .private_segment_fixed_size: 0
    .sgpr_count:     108
    .sgpr_spill_count: 44
    .symbol:         _Z8mega_fwd6Params.kd
    .uniform_work_group_size: 1
    .uses_dynamic_stack: false
    .vgpr_count:     256
    .vgpr_spill_count: 0
    .wavefront_size: 64
